# MoBA attention chunk loop: s_setprio 1/0 pairs around the QK and PV MFMA blocks (per-segment priority in attention)
# speedup vs baseline: 1.0115x; 1.0115x over previous
.LBB0_798:
	v_cvt_pk_bf16_f32 v234, v198, v202
	v_cvt_pk_bf16_f32 v235, v196, v200
	v_cvt_pk_bf16_f32 v236, v190, v194
	v_cvt_pk_bf16_f32 v237, v188, v192
	v_cvt_pk_bf16_f32 v238, v199, v203
	v_cvt_pk_bf16_f32 v239, v197, v201
	v_cvt_pk_bf16_f32 v240, v191, v195
	v_cvt_pk_bf16_f32 v241, v189, v193
	v_cvt_pk_bf16_f32 v242, v182, v186
	v_cvt_pk_bf16_f32 v243, v180, v184
	v_cvt_pk_bf16_f32 v244, v174, v178
	v_cvt_pk_bf16_f32 v245, v36, v176
	v_cvt_pk_bf16_f32 v246, v183, v187
	v_cvt_pk_bf16_f32 v247, v181, v185
	v_cvt_pk_bf16_f32 v248, v175, v179
	v_cvt_pk_bf16_f32 v249, v37, v177
	ds_read_b128 v[120:123], v169
	ds_read_b128 v[116:119], v169 offset:64
	ds_read_b128 v[132:135], v169 offset:2304
	ds_read_b128 v[112:115], v169 offset:2368
	ds_read_b128 v[128:131], v169 offset:4608
	ds_read_b128 v[108:111], v169 offset:4672
	ds_read_b128 v[124:127], v169 offset:6912
	ds_read_b128 v[104:107], v169 offset:6976
	v_pk_add_f32 v[190:191], v[190:191], v[194:195]
	v_pk_add_f32 v[188:189], v[188:189], v[192:193]
	v_pk_add_f32 v[182:183], v[182:183], v[186:187]
	v_pk_add_f32 v[180:181], v[180:181], v[184:185]
	v_pk_add_f32 v[190:191], v[190:191], v[188:189]
	v_pk_add_f32 v[192:193], v[182:183], v[180:181]
	v_pk_add_f32 v[194:195], v[174:175], v[178:179]
	v_pk_add_f32 v[36:37], v[36:37], v[176:177]
	ds_read_b128 v[174:177], v171 offset:64
	ds_read_b128 v[178:181], v171 offset:8512
	ds_read_b128 v[182:185], v171 offset:16960
	ds_read_b128 v[186:189], v171 offset:25408
	v_pk_add_f32 v[198:199], v[198:199], v[202:203]
	v_pk_add_f32 v[196:197], v[196:197], v[200:201]
	v_pk_add_f32 v[36:37], v[194:195], v[36:37]
	v_pk_add_f32 v[196:197], v[198:199], v[196:197]
	s_nop 0
	v_pk_add_f32 v[172:173], v[172:173], v[196:197]
	s_nop 0
	v_pk_add_f32 v[172:173], v[190:191], v[172:173]
	s_nop 0
	v_pk_add_f32 v[172:173], v[192:193], v[172:173]
	s_setprio 1
	s_waitcnt lgkmcnt(14)
	v_mfma_f32_16x16x32_bf16 v[84:87], v[100:103], v[234:237], v[84:87]
	v_mfma_f32_16x16x32_bf16 v[60:63], v[100:103], v[238:241], v[60:63]
	v_mfma_f32_16x16x32_bf16 v[80:83], v[96:99], v[234:237], v[80:83]
	v_mfma_f32_16x16x32_bf16 v[68:71], v[96:99], v[238:241], v[68:71]
	s_waitcnt lgkmcnt(13)
	v_mfma_f32_16x16x32_bf16 v[76:79], v[92:95], v[234:237], v[76:79]
	v_mfma_f32_16x16x32_bf16 v[64:67], v[92:95], v[238:241], v[64:67]
	s_waitcnt lgkmcnt(12)
	v_mfma_f32_16x16x32_bf16 v[72:75], v[88:91], v[234:237], v[72:75]
	v_mfma_f32_16x16x32_bf16 v[56:59], v[88:91], v[238:241], v[56:59]
	s_waitcnt lgkmcnt(3)
	v_mfma_f32_16x16x32_bf16 v[84:87], v[174:177], v[242:245], v[84:87]
	v_add_f32_e64 v172, v36, v172
	v_add_f32_e64 v173, v37, v173
	v_mfma_f32_16x16x32_bf16 v[60:63], v[174:177], v[246:249], v[60:63]
	s_waitcnt lgkmcnt(2)
	v_mfma_f32_16x16x32_bf16 v[80:83], v[178:181], v[242:245], v[80:83]
	v_mfma_f32_16x16x32_bf16 v[68:71], v[178:181], v[246:249], v[68:71]
	s_waitcnt lgkmcnt(1)
	v_mfma_f32_16x16x32_bf16 v[76:79], v[182:185], v[242:245], v[76:79]
	v_mfma_f32_16x16x32_bf16 v[64:67], v[182:185], v[246:249], v[64:67]
	s_waitcnt lgkmcnt(0)
	v_mfma_f32_16x16x32_bf16 v[72:75], v[186:189], v[242:245], v[72:75]
	v_mfma_f32_16x16x32_bf16 v[56:59], v[186:189], v[246:249], v[56:59]
	s_setprio 0
	s_sub_i32 s26, s26, 64
	v_add_u32_e32 v169, 0x2400, v169
	s_cmpk_eq_i32 s26, 0xff40
	v_add_u32_e32 v171, 0x80, v171
	s_cbranch_scc1 .LBB0_802
.LBB0_799:
	s_setprio 1
	s_waitcnt lgkmcnt(7)
	v_mfma_f32_16x16x32_bf16 v[88:91], v[120:123], v[44:47], v[32:35]
	v_mfma_f32_16x16x32_bf16 v[92:95], v[120:123], v[52:55], v[32:35]
	s_waitcnt lgkmcnt(5)
	v_mfma_f32_16x16x32_bf16 v[96:99], v[132:135], v[44:47], v[32:35]
	v_mfma_f32_16x16x32_bf16 v[100:103], v[132:135], v[52:55], v[32:35]
	s_waitcnt lgkmcnt(3)
	v_mfma_f32_16x16x32_bf16 v[120:123], v[128:131], v[44:47], v[32:35]
	v_mfma_f32_16x16x32_bf16 v[128:131], v[128:131], v[52:55], v[32:35]
	s_waitcnt lgkmcnt(1)
	v_mfma_f32_16x16x32_bf16 v[132:135], v[124:127], v[44:47], v[32:35]
	v_mfma_f32_16x16x32_bf16 v[124:127], v[124:127], v[52:55], v[32:35]
	v_mfma_f32_16x16x32_bf16 v[174:177], v[116:119], v[40:43], v[88:91]
	v_mfma_f32_16x16x32_bf16 v[178:181], v[112:115], v[40:43], v[96:99]
	v_mfma_f32_16x16x32_bf16 v[116:119], v[116:119], v[48:51], v[92:95]
	v_mfma_f32_16x16x32_bf16 v[112:115], v[112:115], v[48:51], v[100:103]
	v_mfma_f32_16x16x32_bf16 v[120:123], v[108:111], v[40:43], v[120:123]
	v_mfma_f32_16x16x32_bf16 v[108:111], v[108:111], v[48:51], v[128:131]
	s_waitcnt lgkmcnt(0)
	v_mfma_f32_16x16x32_bf16 v[128:131], v[104:107], v[40:43], v[132:135]
	v_mfma_f32_16x16x32_bf16 v[104:107], v[104:107], v[48:51], v[124:127]
	s_setprio 0
	ds_read_b128 v[100:103], v171
	ds_read_b128 v[96:99], v171 offset:8448
	ds_read_b128 v[92:95], v171 offset:16896
	ds_read_b128 v[88:91], v171 offset:25344
	v_exp_f32_e32 v198, v174
	v_exp_f32_e32 v199, v116
	v_exp_f32_e32 v202, v175
	v_exp_f32_e32 v203, v117
	v_exp_f32_e32 v196, v176
	v_exp_f32_e32 v197, v118
	v_exp_f32_e32 v200, v177
	v_exp_f32_e32 v201, v119
	v_exp_f32_e32 v190, v178
	v_exp_f32_e32 v191, v112
	v_exp_f32_e32 v194, v179
	v_exp_f32_e32 v195, v113
	v_exp_f32_e32 v188, v180
	v_exp_f32_e32 v189, v114
	v_exp_f32_e32 v192, v181
	v_exp_f32_e32 v193, v115
	v_exp_f32_e32 v182, v120
	v_exp_f32_e32 v183, v108
	v_exp_f32_e32 v186, v121
	v_exp_f32_e32 v187, v109
	v_exp_f32_e32 v180, v122
	v_exp_f32_e32 v181, v110
	v_exp_f32_e32 v184, v123
	v_exp_f32_e32 v185, v111
	v_exp_f32_e32 v174, v128
	v_exp_f32_e32 v175, v104
	v_exp_f32_e32 v178, v129
	v_exp_f32_e32 v179, v105
	v_exp_f32_e32 v36, v130
	v_exp_f32_e32 v37, v106
	v_exp_f32_e32 v176, v131
	v_exp_f32_e32 v177, v107
	s_and_b64 vcc, exec, s[0:1]
	s_cbranch_vccz .LBB0_798
	v_add_u32_e32 v104, s26, v233
	v_add_u32_e32 v105, s26, v232
	v_cmp_lt_i32_e32 vcc, -1, v104
	s_nop 1
	v_cndmask_b32_e32 v198, 0, v198, vcc
	v_cmp_lt_i32_e32 vcc, -1, v105
	s_nop 1
	v_cndmask_b32_e32 v199, 0, v199, vcc
	v_cmp_lt_i32_e32 vcc, 0, v104
	s_nop 1
	v_cndmask_b32_e32 v202, 0, v202, vcc
	v_cmp_lt_i32_e32 vcc, 0, v105
	s_nop 1
	v_cndmask_b32_e32 v203, 0, v203, vcc
	v_cmp_lt_i32_e32 vcc, 1, v104
	s_nop 1
	v_cndmask_b32_e32 v196, 0, v196, vcc
	v_cmp_lt_i32_e32 vcc, 1, v105
	s_nop 1
	v_cndmask_b32_e32 v197, 0, v197, vcc
	v_cmp_lt_i32_e32 vcc, 2, v104
	s_nop 1
	v_cndmask_b32_e32 v200, 0, v200, vcc
	v_cmp_lt_i32_e32 vcc, 2, v105
	s_nop 1
	v_cndmask_b32_e32 v201, 0, v201, vcc
	v_cmp_lt_i32_e32 vcc, 15, v104
	s_nop 1
	v_cndmask_b32_e32 v190, 0, v190, vcc
	v_cmp_lt_i32_e32 vcc, 15, v105
	s_nop 1
	v_cndmask_b32_e32 v191, 0, v191, vcc
	v_cmp_lt_i32_e32 vcc, 16, v104
	s_nop 1
	v_cndmask_b32_e32 v194, 0, v194, vcc
	v_cmp_lt_i32_e32 vcc, 16, v105
	s_nop 1
	v_cndmask_b32_e32 v195, 0, v195, vcc
	v_cmp_lt_i32_e32 vcc, 17, v104
	s_nop 1
	v_cndmask_b32_e32 v188, 0, v188, vcc
	v_cmp_lt_i32_e32 vcc, 17, v105
	s_nop 1
	v_cndmask_b32_e32 v189, 0, v189, vcc
	v_cmp_lt_i32_e32 vcc, 18, v104
	s_nop 1
	v_cndmask_b32_e32 v192, 0, v192, vcc
	v_cmp_lt_i32_e32 vcc, 18, v105
	s_nop 1
	v_cndmask_b32_e32 v193, 0, v193, vcc
	v_cmp_lt_i32_e32 vcc, 31, v104
	s_nop 1
	v_cndmask_b32_e32 v182, 0, v182, vcc
	v_cmp_lt_i32_e32 vcc, 31, v105
	s_nop 1
	v_cndmask_b32_e32 v183, 0, v183, vcc
	v_cmp_lt_i32_e32 vcc, 32, v104
	s_nop 1
	v_cndmask_b32_e32 v186, 0, v186, vcc
	v_cmp_lt_i32_e32 vcc, 32, v105
	s_nop 1
	v_cndmask_b32_e32 v187, 0, v187, vcc
	v_cmp_lt_i32_e32 vcc, 33, v104
	s_nop 1
	v_cndmask_b32_e32 v180, 0, v180, vcc
	v_cmp_lt_i32_e32 vcc, 33, v105
	s_nop 1
	v_cndmask_b32_e32 v181, 0, v181, vcc
	v_cmp_lt_i32_e32 vcc, 34, v104
	s_nop 1
	v_cndmask_b32_e32 v184, 0, v184, vcc
	v_cmp_lt_i32_e32 vcc, 34, v105
	s_nop 1
	v_cndmask_b32_e32 v185, 0, v185, vcc
	v_cmp_lt_i32_e32 vcc, 47, v104
	s_nop 1
	v_cndmask_b32_e32 v174, 0, v174, vcc
	v_cmp_lt_i32_e32 vcc, 47, v105
	s_nop 1
	v_cndmask_b32_e32 v175, 0, v175, vcc
	v_cmp_lt_i32_e32 vcc, 48, v104
	s_nop 1
	v_cndmask_b32_e32 v178, 0, v178, vcc
	v_cmp_lt_i32_e32 vcc, 48, v105
	s_nop 1
	v_cndmask_b32_e32 v179, 0, v179, vcc
	v_cmp_lt_i32_e32 vcc, 49, v104
	s_nop 1
	v_cndmask_b32_e32 v36, 0, v36, vcc
	v_cmp_lt_i32_e32 vcc, 49, v105
	s_nop 1
	v_cndmask_b32_e32 v37, 0, v37, vcc
	v_cmp_lt_i32_e32 vcc, 50, v104
	s_nop 1
	v_cndmask_b32_e32 v176, 0, v176, vcc
	v_cmp_lt_i32_e32 vcc, 50, v105
	s_nop 1
	v_cndmask_b32_e32 v177, 0, v177, vcc
	s_branch .LBB0_798
